# static s_setprio 1 for waves 0-3 (older half) before the attention loop, no per-segment priority flips
# speedup vs baseline: 1.0096x; 1.0006x over previous
; #define AT_BAR() do { __builtin_amdgcn_sched_barrier(0); asm volatile("s_waitcnt lgkmcnt(0)\n\ts_barrier" ::: "memory"); __builtin_amdgcn_sched_barrier(0); } while (0)
; __device__ __forceinline__ void attn_phase(LAS unsigned char* lds, const bf16_t* Qb, const bf16_t* Kimg, const bf16_t* Vimg, bf16_t* AB, int bid, int G, int wave_k) {
;     ...
;         int b_prev = 2 * AT_BUF, b_cur = 0, b_next = AT_BUF;
;         AT_ISSUE(0, 0); AT_ISSUE(1, AT_BUF);
;         asm volatile("s_waitcnt vmcnt(0)" ::: "memory"); AT_BAR();
;         if (grpB) AT_BAR();
;         for (int t = 0; t < 256; ++t) {
.LBB0_962:
	s_waitcnt lgkmcnt(0)
	s_barrier
	s_add_u32 s0, s0, 0x6000
	s_addc_u32 s1, s1, 0
	s_mul_i32 s16, s55, 3
	s_add_u32 s18, s18, s16
	s_addc_u32 s19, s19, 0
	s_add_u32 s20, s20, 0x9000
	s_addc_u32 s21, s21, 0
	s_mov_b32 s61, 1
	s_mov_b32 s63, 0xa000
	s_movk_i32 s62, 0x5000
	s_mov_b32 s16, 0
	v_mov_b32_e32 v65, v64
	v_mov_b32_e32 v66, v64
	v_mov_b32_e32 v67, v64
	v_mov_b32_e32 v68, v64
	v_mov_b32_e32 v69, v64
	v_mov_b32_e32 v70, v64
	v_mov_b32_e32 v71, v64
	v_mov_b32_e32 v72, v64
	v_mov_b32_e32 v73, v64
	v_mov_b32_e32 v74, v64
	v_mov_b32_e32 v75, v64
	v_mov_b32_e32 v76, v64
	v_mov_b32_e32 v77, v64
	v_mov_b32_e32 v78, v64
	v_mov_b32_e32 v79, v64
	v_mov_b32_e32 v234, v223
	v_mov_b32_e32 v237, v222
	s_bitcmp1_b32 s42, 0
	s_cbranch_scc1 .Lat_prio_skip
	s_setprio 1
